# v10 + final rmsnorm row loop de-serialised: the 8 loop-invariant g_final vectors are loaded once before the loop instead of one load + vmcnt(0) per 16-byte store (the wait also drained the previous st
# baseline (speedup 1.0000x reference)
; __device__ __forceinline__ float bf_lo(unsigned w) { return __uint_as_float(w << 16); }
; __device__ __forceinline__ float bf_hi(unsigned w) { return __uint_as_float(w & 0xffff0000u); }
; template <bool MOD, bool SRC16>
; __device__ __forceinline__ void norm_rows(const float* src, int nrows, int tok0, const float* g, const float* ada, int sh_off, int sc_off, bf16* dst, float* dstf, int gw, int NGW, int lane_in) {
;     ...
;     for (int m = gw; m < nrows; m += NGW) {
;         f32x4 v[8]; float s = 0.f;
;         if (SRC16) { const v4u* xh = (const v4u*)((const bf16*)src + (size_t)m * 4096) + lane;
; #pragma unroll
;             for (int j = 0; j < 4; ++j) { const v4u w = xh[64 * j]; v[2 * j] = (f32x4){pg8::bf_lo(w.x), pg8::bf_hi(w.x), pg8::bf_lo(w.y), pg8::bf_hi(w.y)}; v[2 * j + 1] = (f32x4){pg8::bf_lo(w.z), pg8::bf_hi(w.z), pg8::bf_lo(w.w), pg8::bf_hi(w.w)}; } }
;         else { const f32x4* xr = (const f32x4*)(src + (size_t)m * DM) + lane;
; #pragma unroll
;             for (int j = 0; j < 8; ++j) v[j] = __builtin_nontemporal_load(xr + 64 * j); }
; #pragma unroll
;         for (int j = 0; j < 8; ++j) { s += (v[j].x * v[j].x + v[j].y * v[j].y) + (v[j].z * v[j].z + v[j].w * v[j].w); }
;         const float r = 1.0f / sqrtf(wave_sum(s) * (1.f / DM) + EPS);
;     ...
;         } else {
; #pragma unroll
;             for (int j = 0; j < 8; ++j) { const int col = SRC16 ? 8 * (lane + 64 * (j >> 1)) + 4 * (j & 1) : 4 * (lane + 64 * j);
;                 const f32x4 gv = *(const f32x4*)(g + col); *(f32x4*)(dstf + (size_t)m * DM + col) = (v[j] * r) * gv; }
;         }
.LBB0_2149:
	s_or_b64 exec, exec, s[0:1]
	v_readlane_b32 s8, v248, 39
	s_cmp_gt_i32 s8, 0xbfff
	s_waitcnt lgkmcnt(0)
	s_barrier
	v_readlane_b32 s9, v248, 40
	s_cbranch_scc1 .LBB0_2152
	v_lshlrev_b32_e32 v12, 3, v192
	v_ashrrev_i32_e32 v13, 31, v12
	v_lshlrev_b64 v[0:1], 2, v[12:13]
	v_add_u32_e32 v4, 0x200, v12
	v_add_u32_e32 v8, 0x400, v12
	v_add_u32_e32 v12, 0x600, v12
	v_readlane_b32 s0, v248, 3
	v_ashrrev_i32_e32 v5, 31, v4
	v_ashrrev_i32_e32 v9, 31, v8
	v_ashrrev_i32_e32 v13, 31, v12
	v_readlane_b32 s1, v248, 4
	v_lshlrev_b64 v[4:5], 2, v[4:5]
	v_lshlrev_b64 v[8:9], 2, v[8:9]
	v_lshlrev_b64 v[12:13], 2, v[12:13]
	s_ashr_i32 s9, s8, 31
	v_readlane_b32 s2, v248, 5
	v_lshl_add_u64 v[2:3], s[0:1], 0, v[0:1]
	v_lshl_add_u64 v[6:7], s[0:1], 0, v[4:5]
	v_lshl_add_u64 v[10:11], s[0:1], 0, v[8:9]
	v_lshl_add_u64 v[14:15], s[0:1], 0, v[12:13]
	s_lshl_b64 s[0:1], s[8:9], 13
	v_readlane_b32 s3, v248, 6
	s_add_u32 s2, s2, s0
	v_ashrrev_i32_e32 v193, 31, v192
	s_addc_u32 s3, s3, s1
	s_ashr_i32 s87, s86, 31
	v_or_b32_e32 v12, 16, v12
	s_lshl_b64 s[4:5], s[86:87], 13
	v_lshlrev_b64 v[16:17], 4, v[192:193]
	v_or_b32_e32 v4, 16, v4
	v_or_b32_e32 v8, 16, v8
	v_mov_b32_e32 v20, 0x358637bd
	s_mov_b32 s6, 0xf800000
	v_mov_b32_e32 v21, 0x260
	global_load_dwordx4 v[100:103], v[2:3], off
	global_load_dwordx4 v[104:107], v[2:3], off offset:16
	global_load_dwordx4 v[108:111], v[2:3], off offset:2048
	global_load_dwordx4 v[112:115], v[6:7], off offset:16
	global_load_dwordx4 v[116:119], v[10:11], off
	global_load_dwordx4 v[120:123], v[10:11], off offset:16
	global_load_dwordx4 v[124:127], v[14:15], off
	global_load_dwordx4 v[128:131], v[14:15], off offset:16
	s_waitcnt vmcnt(0)
.LBB0_2151:
	v_lshl_add_u64 v[18:19], s[2:3], 0, v[16:17]
	global_load_dwordx4 v[26:29], v[18:19], off offset:1024
	global_load_dwordx4 v[30:33], v[18:19], off offset:2048
	global_load_dwordx4 v[34:37], v[18:19], off offset:3072
	global_load_dwordx4 v[38:41], v[18:19], off
	v_lshl_add_u64 v[42:43], s[2:3], 0, v[0:1]
	s_add_i32 s8, s8, s86
	s_waitcnt vmcnt(3)
	v_lshlrev_b32_e32 v44, 16, v28
	v_and_b32_e32 v45, 0xffff0000, v28
	s_waitcnt vmcnt(2)
	v_lshlrev_b32_e32 v28, 16, v30
	s_waitcnt vmcnt(0)
	v_lshlrev_b32_e32 v49, 16, v40
	v_and_b32_e32 v51, 0xffff0000, v40
	v_and_b32_e32 v50, 0xffff0000, v38
	v_lshlrev_b32_e32 v53, 16, v41
	v_and_b32_e32 v41, 0xffff0000, v41
	v_and_b32_e32 v40, 0xffff0000, v39
	v_lshlrev_b32_e32 v48, 16, v38
	v_lshlrev_b32_e32 v52, 16, v39
	v_lshlrev_b32_e32 v39, 16, v27
	v_lshlrev_b32_e32 v38, 16, v26
	v_and_b32_e32 v27, 0xffff0000, v27
	v_and_b32_e32 v26, 0xffff0000, v26
	v_pk_mul_f32 v[58:59], v[50:51], v[50:51]
	v_pk_mul_f32 v[60:61], v[40:41], v[40:41]
	v_lshlrev_b32_e32 v54, 16, v29
	v_pk_mul_f32 v[62:63], v[26:27], v[26:27]
	v_pk_fma_f32 v[58:59], v[48:49], v[48:49], v[58:59]
	v_pk_fma_f32 v[60:61], v[52:53], v[52:53], v[60:61]
	v_and_b32_e32 v55, 0xffff0000, v29
	v_mul_f32_e32 v29, v44, v44
	v_mul_f32_e32 v65, v45, v45
	v_mul_f32_e32 v66, v54, v54
	v_mov_b32_e32 v64, v28
	v_pk_fma_f32 v[62:63], v[38:39], v[38:39], v[62:63]
	v_pk_add_f32 v[58:59], v[58:59], v[60:61]
	v_and_b32_e32 v82, 0xffff0000, v30
	v_lshlrev_b32_e32 v30, 16, v31
	v_and_b32_e32 v31, 0xffff0000, v31
	v_pk_fma_f32 v[66:67], v[54:55], v[54:55], v[66:67] op_sel_hi:[1,1,0]
	v_pk_add_f32 v[64:65], v[28:29], v[64:65]
	v_pk_add_f32 v[60:61], v[62:63], v[62:63] op_sel_hi:[0,1]
	v_pk_add_f32 v[58:59], v[58:59], v[58:59] op_sel_hi:[0,1]
	v_lshlrev_b32_e32 v57, 16, v33
	v_lshlrev_b32_e32 v56, 16, v32
	v_and_b32_e32 v33, 0xffff0000, v33
	v_and_b32_e32 v32, 0xffff0000, v32
	v_mul_f32_e32 v68, v28, v28
	v_mul_f32_e32 v66, v82, v82
	v_mov_b32_e32 v69, v65
	v_mul_f32_e32 v60, v31, v31
	v_mul_f32_e32 v58, v30, v30
	v_lshlrev_b32_e32 v46, 16, v34
	v_and_b32_e32 v47, 0xffff0000, v34
	v_lshlrev_b32_e32 v18, 16, v36
	v_lshlrev_b32_e32 v34, 16, v35
	v_pk_mul_f32 v[70:71], v[32:33], v[32:33]
	v_pk_add_f32 v[64:65], v[68:69], v[66:67]
	v_pk_add_f32 v[58:59], v[58:59], v[60:61]
	v_and_b32_e32 v35, 0xffff0000, v35
	v_mul_f32_e32 v19, v46, v46
	v_mul_f32_e32 v73, v47, v47
	v_mul_f32_e32 v74, v34, v34
	v_mov_b32_e32 v72, v18
	v_pk_fma_f32 v[70:71], v[56:57], v[56:57], v[70:71]
	v_pk_add_f32 v[58:59], v[64:65], v[58:59]
	v_and_b32_e32 v83, 0xffff0000, v36
	v_lshlrev_b32_e32 v36, 16, v37
	v_and_b32_e32 v37, 0xffff0000, v37
	v_pk_fma_f32 v[74:75], v[34:35], v[34:35], v[74:75] op_sel_hi:[1,1,0]
	v_pk_add_f32 v[72:73], v[18:19], v[72:73]
	v_pk_add_f32 v[62:63], v[70:71], v[70:71] op_sel_hi:[0,1]
	v_pk_add_f32 v[58:59], v[58:59], v[58:59] op_sel_hi:[0,1]
	v_mul_f32_e32 v76, v18, v18
	v_mul_f32_e32 v74, v83, v83
	v_mov_b32_e32 v77, v73
	v_mul_f32_e32 v62, v36, v36
	v_mul_f32_e32 v58, v37, v37
	v_pk_add_f32 v[66:67], v[76:77], v[74:75]
	v_pk_add_f32 v[58:59], v[62:63], v[58:59]
	v_mov_b32_e32 v81, v40
	v_pk_add_f32 v[58:59], v[66:67], v[58:59]
	v_mov_b32_e32 v78, v48
	v_add_f32_e32 v19, v58, v59
	ds_bpermute_b32 v29, v195, v19
	v_mov_b32_e32 v79, v50
	v_mov_b32_e32 v80, v52
	s_waitcnt lgkmcnt(0)
; __device__ __forceinline__ unsigned pk2(float lo, float hi) { return f2bf(lo) | (f2bf(hi) << 16); }
; __device__ __forceinline__ float wave_sum(float v) {
; #pragma unroll
;     for (int o = 1; o < 64; o <<= 1) v += __shfl_xor(v, o);
;     return v;
; }
; template <bool MOD, bool SRC16>
; __device__ __forceinline__ void norm_rows(const float* src, int nrows, int tok0, const float* g, const float* ada, int sh_off, int sc_off, bf16* dst, float* dstf, int gw, int NGW, int lane_in) {
;     ...
;         const float r = 1.0f / sqrtf(wave_sum(s) * (1.f / DM) + EPS);
;         if (MOD) {
;             const int b = batch_of(tok0 + m); const float* ab = ada + (size_t)b * ADAW;
;             f32x4 y[8];
; #pragma unroll
;             for (int j = 0; j < 8; ++j) { const int col = SRC16 ? 8 * (lane + 64 * (j >> 1)) + 4 * (j & 1) : 4 * (lane + 64 * j);
;                 const f32x4 gv = *(const f32x4*)(g + col), sc = *(const f32x4*)(ab + sc_off + col), sh = *(const f32x4*)(ab + sh_off + col);
;                 y[j] = (v[j] * r) * gv * (sc + 1.0f) + sh; }
;             if (SRC16) { v4u* o16 = (v4u*)(dst + (size_t)m * DM) + lane;
; #pragma unroll
;                 for (int j = 0; j < 4; ++j) { v4u w; w.x = pk2(y[2 * j].x, y[2 * j].y); w.y = pk2(y[2 * j].z, y[2 * j].w); w.z = pk2(y[2 * j + 1].x, y[2 * j + 1].y); w.w = pk2(y[2 * j + 1].z, y[2 * j + 1].w); o16[64 * j] = w; } }
;             else { v2u* o8 = (v2u*)(dst + (size_t)m * DM) + lane;
; #pragma unroll
;                 for (int j = 0; j < 8; ++j) { v2u w; w.x = pk2(y[j].x, y[j].y); w.y = pk2(y[j].z, y[j].w); o8[64 * j] = w; } }
;         } else {
; #pragma unroll
;             for (int j = 0; j < 8; ++j) { const int col = SRC16 ? 8 * (lane + 64 * (j >> 1)) + 4 * (j & 1) : 4 * (lane + 64 * j);
;                 const f32x4 gv = *(const f32x4*)(g + col); *(f32x4*)(dstf + (size_t)m * DM + col) = (v[j] * r) * gv; }
;         }
	v_add_f32_e32 v19, v19, v29
	ds_bpermute_b32 v29, v202, v19
	s_waitcnt lgkmcnt(0)
	v_add_f32_e32 v19, v19, v29
	ds_bpermute_b32 v29, v203, v19
	s_waitcnt lgkmcnt(0)
	v_add_f32_e32 v19, v19, v29
	ds_bpermute_b32 v29, v204, v19
	s_waitcnt lgkmcnt(0)
	v_add_f32_e32 v19, v19, v29
	ds_bpermute_b32 v29, v205, v19
	s_waitcnt lgkmcnt(0)
	v_add_f32_e32 v19, v19, v29
	ds_bpermute_b32 v29, v206, v19
	s_waitcnt lgkmcnt(0)
	v_add_f32_e32 v19, v19, v29
	v_fmamk_f32 v19, v19, 0x3a000000, v20
	v_mul_f32_e32 v29, 0x4f800000, v19
	v_cmp_gt_f32_e32 vcc, s6, v19
	s_nop 1
	v_cndmask_b32_e32 v19, v19, v29, vcc
	v_sqrt_f32_e32 v29, v19
	s_nop 0
	v_add_u32_e32 v40, -1, v29
	v_add_u32_e32 v48, 1, v29
	v_fma_f32 v50, -v40, v29, v19
	v_fma_f32 v52, -v48, v29, v19
	v_cmp_ge_f32_e64 s[0:1], 0, v50
	s_nop 1
	v_cndmask_b32_e64 v29, v29, v40, s[0:1]
	v_cmp_lt_f32_e64 s[0:1], 0, v52
	s_nop 1
	v_cndmask_b32_e64 v29, v29, v48, s[0:1]
	v_mul_f32_e32 v40, 0x37800000, v29
	v_cndmask_b32_e32 v29, v29, v40, vcc
	v_cmp_class_f32_e32 vcc, v19, v21
	s_nop 1
	v_cndmask_b32_e32 v19, v29, v19, vcc
	v_div_scale_f32 v29, s[0:1], v19, v19, 1.0
	v_rcp_f32_e32 v48, v29
	v_div_scale_f32 v40, vcc, 1.0, v19, 1.0
	v_fma_f32 v50, -v29, v48, 1.0
	v_fmac_f32_e32 v48, v50, v48
	v_mul_f32_e32 v50, v40, v48
	v_fma_f32 v52, -v29, v50, v40
	v_fmac_f32_e32 v50, v52, v48
	v_fma_f32 v29, -v29, v50, v40
	v_div_fmas_f32 v29, v29, v48, v50
	v_div_fixup_f32 v48, v29, v19, 1.0
	v_pk_mul_f32 v[58:59], v[78:79], v[48:49] op_sel_hi:[1,0]
	v_pk_mul_f32 v[60:61], v[80:81], v[48:49] op_sel_hi:[1,0]
	v_pk_mul_f32 v[22:23], v[100:101], v[58:59]
	v_pk_mul_f32 v[24:25], v[102:103], v[60:61]
	global_store_dwordx4 v[42:43], v[22:25], off
	v_mov_b32_e32 v40, v53
	v_mov_b32_e32 v50, v49
	v_pk_mul_f32 v[40:41], v[40:41], v[48:49] op_sel_hi:[1,0]
	v_pk_mul_f32 v[50:51], v[50:51], v[48:49] op_sel_hi:[1,0]
	v_mov_b32_e32 v29, v82
	v_pk_mul_f32 v[30:31], v[30:31], v[48:49] op_sel_hi:[1,0]
	v_pk_mul_f32 v[28:29], v[28:29], v[48:49] op_sel_hi:[1,0]
	v_mov_b32_e32 v19, v83
	v_pk_mul_f32 v[18:19], v[18:19], v[48:49] op_sel_hi:[1,0]
	v_pk_mul_f32 v[132:133], v[104:105], v[50:51]
	v_pk_mul_f32 v[134:135], v[106:107], v[40:41]
	global_store_dwordx4 v[42:43], v[132:135], off offset:16
	v_mov_b32_e32 v40, v39
	v_mov_b32_e32 v41, v27
	v_mov_b32_e32 v39, v26
	v_pk_mul_f32 v[26:27], v[48:49], v[40:41] op_sel_hi:[0,1]
	v_pk_mul_f32 v[38:39], v[48:49], v[38:39] op_sel_hi:[0,1]
	v_pk_mul_f32 v[40:41], v[44:45], v[48:49] op_sel_hi:[1,0]
	v_pk_mul_f32 v[22:23], v[108:109], v[38:39]
	v_pk_mul_f32 v[24:25], v[110:111], v[26:27]
	global_store_dwordx4 v[42:43], v[22:25], off offset:2048
	v_pk_mul_f32 v[38:39], v[54:55], v[48:49] op_sel_hi:[1,0]
	v_lshl_add_u64 v[26:27], s[2:3], 0, v[4:5]
	v_pk_mul_f32 v[132:133], v[112:113], v[40:41]
	v_pk_mul_f32 v[134:135], v[114:115], v[38:39]
	global_store_dwordx4 v[26:27], v[132:135], off
	v_lshl_add_u64 v[26:27], s[2:3], 0, v[8:9]
	v_pk_mul_f32 v[22:23], v[116:117], v[28:29]
	v_pk_mul_f32 v[24:25], v[118:119], v[30:31]
	global_store_dwordx4 v[26:27], v[22:25], off offset:-16
	v_mov_b32_e32 v28, v57
	v_mov_b32_e32 v29, v33
	v_mov_b32_e32 v57, v32
	v_pk_mul_f32 v[28:29], v[48:49], v[28:29] op_sel_hi:[0,1]
	v_pk_mul_f32 v[30:31], v[48:49], v[56:57] op_sel_hi:[0,1]
	v_pk_mul_f32 v[132:133], v[120:121], v[30:31]
	v_pk_mul_f32 v[134:135], v[122:123], v[28:29]
	global_store_dwordx4 v[26:27], v[132:135], off
	v_pk_mul_f32 v[28:29], v[34:35], v[48:49] op_sel_hi:[1,0]
	v_pk_mul_f32 v[30:31], v[46:47], v[48:49] op_sel_hi:[1,0]
	v_lshl_add_u64 v[26:27], s[2:3], 0, v[12:13]
	s_add_u32 s2, s2, s4
	s_addc_u32 s3, s3, s5
	s_cmp_lt_i32 s8, 0xc000
	v_pk_mul_f32 v[22:23], v[124:125], v[30:31]
	v_pk_mul_f32 v[24:25], v[126:127], v[28:29]
	global_store_dwordx4 v[26:27], v[22:25], off offset:-16
	v_pk_mul_f32 v[28:29], v[36:37], v[48:49] op_sel_hi:[1,0]
	v_pk_mul_f32 v[132:133], v[128:129], v[18:19]
	v_pk_mul_f32 v[134:135], v[130:131], v[28:29]
	global_store_dwordx4 v[26:27], v[132:135], off
	s_cbranch_scc1 .LBB0_2151
